# P1 pipelined x loads + indexer score select by branch tree + attention QK^T K-fragment reads double-buffered (counted lgkmcnt)
# speedup vs baseline: 1.0092x; 1.0092x over previous
.LBB0_1163:
	v_max_f32 v192, 0, v80
	v_max_f32 v193, 0, v81
	v_max_f32 v194, 0, v65
	v_max_f32 v195, 0, v49
	v_max_f32 v196, 0, v33
	v_fma_f32 v192, v124, v192, 0
	v_fmac_f32_e32 v192, v125, v193
	v_max_f32 v193, 0, v64
	v_fma_f32 v193, v120, v193, 0
	v_fmac_f32_e32 v193, v121, v194
	v_max_f32 v194, 0, v48
	v_fma_f32 v194, v124, v194, 0
	v_fmac_f32_e32 v194, v125, v195
	v_max_f32 v195, 0, v32
	v_fma_f32 v195, v120, v195, 0
	v_fmac_f32_e32 v195, v121, v196
	v_max_f32 v196, 0, v82
	v_fmac_f32_e32 v192, v126, v196
	v_max_f32 v196, 0, v66
	v_fmac_f32_e32 v193, v122, v196
	v_max_f32 v196, 0, v50
	v_fmac_f32_e32 v194, v126, v196
	v_max_f32 v196, 0, v34
	v_fmac_f32_e32 v195, v122, v196
	v_max_f32 v196, 0, v83
	v_fmac_f32_e32 v192, v127, v196
	v_max_f32 v196, 0, v67
	v_fmac_f32_e32 v193, v123, v196
	v_max_f32 v196, 0, v51
	v_fmac_f32_e32 v194, v127, v196
	v_max_f32 v196, 0, v35
	v_fmac_f32_e32 v195, v123, v196
	v_max_f32 v196, 0, v84
	v_fmac_f32_e32 v192, v116, v196
	v_max_f32 v196, 0, v68
	v_fmac_f32_e32 v193, v112, v196
	v_max_f32 v196, 0, v52
	v_fmac_f32_e32 v194, v116, v196
	v_max_f32 v196, 0, v36
	v_fmac_f32_e32 v195, v112, v196
	v_max_f32 v196, 0, v85
	v_fmac_f32_e32 v192, v117, v196
	v_max_f32 v196, 0, v69
	v_fmac_f32_e32 v193, v113, v196
	v_max_f32 v196, 0, v53
	v_fmac_f32_e32 v194, v117, v196
	v_max_f32 v196, 0, v37
	v_fmac_f32_e32 v195, v113, v196
	v_max_f32 v196, 0, v86
	v_fmac_f32_e32 v192, v118, v196
	v_max_f32 v196, 0, v70
	v_fmac_f32_e32 v193, v114, v196
	v_max_f32 v196, 0, v54
	v_fmac_f32_e32 v194, v118, v196
	v_max_f32 v196, 0, v38
	v_fmac_f32_e32 v195, v114, v196
	v_max_f32 v196, 0, v87
	v_fmac_f32_e32 v192, v119, v196
	v_max_f32 v196, 0, v71
	v_fmac_f32_e32 v193, v115, v196
	v_max_f32 v196, 0, v55
	v_fmac_f32_e32 v194, v119, v196
	v_max_f32 v196, 0, v39
	v_fmac_f32_e32 v195, v115, v196
	v_max_f32 v196, 0, v88
	v_fmac_f32_e32 v192, v108, v196
	v_max_f32 v196, 0, v72
	v_fmac_f32_e32 v193, v104, v196
	v_max_f32 v196, 0, v56
	v_fmac_f32_e32 v194, v108, v196
	v_max_f32 v196, 0, v40
	s_nop 0
	v_fmac_f32_e32 v195, v104, v196
	v_max_f32 v196, 0, v89
	s_nop 0
	v_fmac_f32_e32 v192, v109, v196
	v_max_f32 v196, 0, v73
	s_nop 0
	v_fmac_f32_e32 v193, v105, v196
	v_max_f32 v196, 0, v57
	s_nop 0
	v_fmac_f32_e32 v194, v109, v196
	v_max_f32 v196, 0, v41
	s_nop 0
	v_fmac_f32_e32 v195, v105, v196
	v_max_f32 v196, 0, v90
	s_nop 0
	v_fmac_f32_e32 v192, v110, v196
	v_max_f32 v196, 0, v74
	s_nop 0
	v_fmac_f32_e32 v193, v106, v196
	v_max_f32 v196, 0, v58
	s_nop 0
	v_fmac_f32_e32 v194, v110, v196
	v_max_f32 v196, 0, v42
	s_nop 0
	v_fmac_f32_e32 v195, v106, v196
	v_max_f32 v196, 0, v91
	s_nop 0
	v_fmac_f32_e32 v192, v111, v196
	v_max_f32 v196, 0, v75
	s_nop 0
	v_fmac_f32_e32 v193, v107, v196
	v_max_f32 v196, 0, v59
	s_nop 0
	v_fmac_f32_e32 v194, v111, v196
	v_max_f32 v196, 0, v43
	s_nop 0
	v_fmac_f32_e32 v195, v107, v196
	v_max_f32 v196, 0, v92
	s_nop 0
	v_fmac_f32_e32 v192, v100, v196
	v_max_f32 v196, 0, v76
	s_nop 0
	v_fmac_f32_e32 v193, v96, v196
	v_max_f32 v196, 0, v60
	s_nop 0
	v_fmac_f32_e32 v194, v100, v196
	v_max_f32 v196, 0, v44
	s_nop 0
	v_fmac_f32_e32 v195, v96, v196
	v_max_f32 v196, 0, v93
	s_nop 0
	v_fmac_f32_e32 v192, v101, v196
	v_max_f32 v196, 0, v77
	s_nop 0
	v_fmac_f32_e32 v193, v97, v196
	v_max_f32 v196, 0, v61
	s_nop 0
	v_fmac_f32_e32 v194, v101, v196
	v_max_f32 v196, 0, v45
	s_nop 0
	v_fmac_f32_e32 v195, v97, v196
	v_max_f32 v196, 0, v94
	s_nop 0
	v_fmac_f32_e32 v192, v102, v196
	v_max_f32 v196, 0, v78
	s_nop 0
	v_fmac_f32_e32 v193, v98, v196
	v_max_f32 v196, 0, v62
	s_nop 0
	v_fmac_f32_e32 v194, v102, v196
	v_max_f32 v196, 0, v46
	s_nop 0
	v_fmac_f32_e32 v195, v98, v196
	v_max_f32 v196, 0, v95
	s_nop 0
	v_fmac_f32_e32 v192, v103, v196
	v_max_f32 v196, 0, v79
	s_nop 0
	v_fmac_f32_e32 v193, v99, v196
	v_max_f32 v196, 0, v63
	s_nop 0
	v_fmac_f32_e32 v194, v103, v196
	v_max_f32 v196, 0, v47
	s_nop 1
	v_permlane32_swap_b32_e32 v192, v194
	v_fmac_f32_e32 v195, v99, v196
	s_nop 1
	v_permlane32_swap_b32_e32 v193, v195
	v_add_f32_e32 v193, v193, v195
	v_add_f32_e32 v192, v192, v194
	s_cmp_lt_u32 s96, 16
	s_cbranch_scc0 .Lidxt1_16_32
	s_cmp_lt_u32 s96, 8
	s_cbranch_scc0 .Lidxt1_8_16
	s_cmp_lt_u32 s96, 4
	s_cbranch_scc0 .Lidxt1_4_8
	s_cmp_lt_u32 s96, 2
	s_cbranch_scc0 .Lidxt1_2_4
	s_cmp_lt_u32 s96, 1
	s_cbranch_scc0 .Lidxt1_1_2
	v_mov_b32_e32 v17, v193
	s_branch .Lidxt1_join
.Lidxt1_1_2:
	v_mov_b32_e32 v0, v193
	s_branch .Lidxt1_join
.Lidxt1_2_4:
	s_cmp_lt_u32 s96, 3
	s_cbranch_scc0 .Lidxt1_3_4
	v_mov_b32_e32 v16, v193
	s_branch .Lidxt1_join
.Lidxt1_3_4:
	v_mov_b32_e32 v1, v193
	s_branch .Lidxt1_join
.Lidxt1_4_8:
	s_cmp_lt_u32 s96, 6
	s_cbranch_scc0 .Lidxt1_6_8
	s_cmp_lt_u32 s96, 5
	s_cbranch_scc0 .Lidxt1_5_6
	v_mov_b32_e32 v18, v193
	s_branch .Lidxt1_join
.Lidxt1_5_6:
	v_mov_b32_e32 v2, v193
	s_branch .Lidxt1_join
.Lidxt1_6_8:
	s_cmp_lt_u32 s96, 7
	s_cbranch_scc0 .Lidxt1_7_8
	v_mov_b32_e32 v19, v193
	s_branch .Lidxt1_join
.Lidxt1_7_8:
	v_mov_b32_e32 v3, v193
	s_branch .Lidxt1_join
.Lidxt1_8_16:
	s_cmp_lt_u32 s96, 12
	s_cbranch_scc0 .Lidxt1_12_16
	s_cmp_lt_u32 s96, 10
	s_cbranch_scc0 .Lidxt1_10_12
	s_cmp_lt_u32 s96, 9
	s_cbranch_scc0 .Lidxt1_9_10
	v_mov_b32_e32 v20, v193
	s_branch .Lidxt1_join
.Lidxt1_9_10:
	v_mov_b32_e32 v4, v193
	s_branch .Lidxt1_join
.Lidxt1_10_12:
	s_cmp_lt_u32 s96, 11
	s_cbranch_scc0 .Lidxt1_11_12
	v_mov_b32_e32 v21, v193
	s_branch .Lidxt1_join
.Lidxt1_11_12:
	v_mov_b32_e32 v5, v193
	s_branch .Lidxt1_join
.Lidxt1_12_16:
	s_cmp_lt_u32 s96, 14
	s_cbranch_scc0 .Lidxt1_14_16
	s_cmp_lt_u32 s96, 13
	s_cbranch_scc0 .Lidxt1_13_14
	v_mov_b32_e32 v22, v193
	s_branch .Lidxt1_join
.Lidxt1_13_14:
	v_mov_b32_e32 v6, v193
	s_branch .Lidxt1_join
.Lidxt1_14_16:
	s_cmp_lt_u32 s96, 15
	s_cbranch_scc0 .Lidxt1_15_16
	v_mov_b32_e32 v23, v193
	s_branch .Lidxt1_join
.Lidxt1_15_16:
	v_mov_b32_e32 v7, v193
	s_branch .Lidxt1_join
.Lidxt1_16_32:
	s_cmp_lt_u32 s96, 24
	s_cbranch_scc0 .Lidxt1_24_32
	s_cmp_lt_u32 s96, 20
	s_cbranch_scc0 .Lidxt1_20_24
	s_cmp_lt_u32 s96, 18
	s_cbranch_scc0 .Lidxt1_18_20
	s_cmp_lt_u32 s96, 17
	s_cbranch_scc0 .Lidxt1_17_18
	v_mov_b32_e32 v24, v193
	s_branch .Lidxt1_join
.Lidxt1_17_18:
	v_mov_b32_e32 v8, v193
	s_branch .Lidxt1_join
.Lidxt1_18_20:
	s_cmp_lt_u32 s96, 19
	s_cbranch_scc0 .Lidxt1_19_20
	v_mov_b32_e32 v25, v193
	s_branch .Lidxt1_join
.Lidxt1_19_20:
	v_mov_b32_e32 v11, v193
	s_branch .Lidxt1_join
.Lidxt1_20_24:
	s_cmp_lt_u32 s96, 22
	s_cbranch_scc0 .Lidxt1_22_24
	s_cmp_lt_u32 s96, 21
	s_cbranch_scc0 .Lidxt1_21_22
	v_mov_b32_e32 v26, v193
	s_branch .Lidxt1_join
.Lidxt1_21_22:
	v_mov_b32_e32 v10, v193
	s_branch .Lidxt1_join
.Lidxt1_22_24:
	s_cmp_lt_u32 s96, 23
	s_cbranch_scc0 .Lidxt1_23_24
	v_mov_b32_e32 v27, v193
	s_branch .Lidxt1_join
.Lidxt1_23_24:
	v_mov_b32_e32 v9, v193
	s_branch .Lidxt1_join
.Lidxt1_24_32:
	s_cmp_lt_u32 s96, 28
	s_cbranch_scc0 .Lidxt1_28_32
	s_cmp_lt_u32 s96, 26
	s_cbranch_scc0 .Lidxt1_26_28
	s_cmp_lt_u32 s96, 25
	s_cbranch_scc0 .Lidxt1_25_26
	v_mov_b32_e32 v28, v193
	s_branch .Lidxt1_join
.Lidxt1_25_26:
	v_mov_b32_e32 v12, v193
	s_branch .Lidxt1_join
.Lidxt1_26_28:
	s_cmp_lt_u32 s96, 27
	s_cbranch_scc0 .Lidxt1_27_28
	v_mov_b32_e32 v29, v193
	s_branch .Lidxt1_join
.Lidxt1_27_28:
	v_mov_b32_e32 v13, v193
	s_branch .Lidxt1_join
.Lidxt1_28_32:
	s_cmp_lt_u32 s96, 30
	s_cbranch_scc0 .Lidxt1_30_32
	s_cmp_lt_u32 s96, 29
	s_cbranch_scc0 .Lidxt1_29_30
	v_mov_b32_e32 v30, v193
	s_branch .Lidxt1_join
.Lidxt1_29_30:
	v_mov_b32_e32 v14, v193
	s_branch .Lidxt1_join
.Lidxt1_30_32:
	s_cmp_lt_u32 s96, 31
	s_cbranch_scc0 .Lidxt1_31_32
	v_mov_b32_e32 v31, v193
	s_branch .Lidxt1_join
.Lidxt1_31_32:
	v_mov_b32_e32 v15, v193
.Lidxt1_join:
	ds_write_b32 v235, v192

.LBB0_1175:
	s_and_b32 s0, s90, 0xc000
	v_add_u32_e32 v237, s0, v225
	v_add_u32_e32 v236, v237, v226
	v_add_u32_e32 v239, v237, v228
	v_add_u32_e32 v238, v237, v227
	ds_read_b128 v[204:207], v236
	ds_read_b128 v[196:199], v238
	v_add_u32_e32 v240, v237, v229
	ds_read_b128 v[200:203], v239
	ds_read_b128 v[192:195], v240
	s_cmp_gt_i32 s92, -1
	s_cselect_b64 s[0:1], -1, 0
	s_and_b64 s[0:1], s[84:85], s[0:1]
	s_andn2_b64 vcc, exec, s[0:1]
	s_cbranch_vccnz .LBB0_1177
	v_max_f32 v80, 0, v80
	v_max_f32 v48, 0, v48
	v_max_f32 v81, 0, v81
	v_max_f32 v49, 0, v49
	v_max_f32 v82, 0, v82
	v_max_f32 v50, 0, v50
	s_nop 0
	v_fma_f32 v80, v124, v80, 0
	v_fma_f32 v48, v124, v48, 0
	v_fmac_f32_e32 v80, v125, v81
	v_fmac_f32_e32 v48, v125, v49
	v_fmac_f32_e32 v80, v126, v82
	v_fmac_f32_e32 v48, v126, v50
	v_max_f32 v83, 0, v83
	v_max_f32 v51, 0, v51
	v_max_f32 v84, 0, v84
	v_max_f32 v52, 0, v52
	v_max_f32 v85, 0, v85
	v_max_f32 v53, 0, v53
	s_nop 0
	v_fmac_f32_e32 v80, v127, v83
	v_fmac_f32_e32 v48, v127, v51
	v_fmac_f32_e32 v80, v116, v84
	v_fmac_f32_e32 v48, v116, v52
	v_fmac_f32_e32 v80, v117, v85
	v_fmac_f32_e32 v48, v117, v53
	v_max_f32 v86, 0, v86
	v_max_f32 v54, 0, v54
	v_max_f32 v87, 0, v87
	v_max_f32 v55, 0, v55
	v_max_f32 v88, 0, v88
	v_max_f32 v56, 0, v56
	s_nop 0
	v_fmac_f32_e32 v80, v118, v86
	v_fmac_f32_e32 v48, v118, v54
	v_fmac_f32_e32 v80, v119, v87
	v_fmac_f32_e32 v48, v119, v55
	v_fmac_f32_e32 v80, v108, v88
	v_fmac_f32_e32 v48, v108, v56
	v_max_f32 v89, 0, v89
	v_max_f32 v57, 0, v57
	v_max_f32 v90, 0, v90
	v_max_f32 v58, 0, v58
	v_max_f32 v91, 0, v91
	v_max_f32 v59, 0, v59
	s_nop 0
	v_fmac_f32_e32 v80, v109, v89
	v_fmac_f32_e32 v48, v109, v57
	v_fmac_f32_e32 v80, v110, v90
	v_fmac_f32_e32 v48, v110, v58
	v_fmac_f32_e32 v80, v111, v91
	v_fmac_f32_e32 v48, v111, v59
	v_max_f32 v92, 0, v92
	v_max_f32 v60, 0, v60
	v_max_f32 v93, 0, v93
	v_max_f32 v61, 0, v61
	v_max_f32 v94, 0, v94
	v_max_f32 v62, 0, v62
	s_nop 0
	v_fmac_f32_e32 v80, v100, v92
	v_fmac_f32_e32 v48, v100, v60
	v_fmac_f32_e32 v80, v101, v93
	v_fmac_f32_e32 v48, v101, v61
	v_fmac_f32_e32 v80, v102, v94
	v_fmac_f32_e32 v48, v102, v62
	v_max_f32 v95, 0, v95
	v_max_f32 v63, 0, v63
	v_max_f32 v32, 0, v32
	v_lshl_add_u32 v49, s92, 8, v224
	v_fmac_f32_e32 v80, v103, v95
	v_fmac_f32_e32 v48, v103, v63
	s_nop 1
	v_permlane32_swap_b32_e32 v80, v48
	v_add_f32_e32 v48, v80, v48
	v_max_f32 v64, 0, v64
	ds_write_b32 v49, v48
	v_fma_f32 v48, v120, v64, 0
	v_fma_f32 v32, v120, v32, 0
	v_max_f32 v65, 0, v65
	v_max_f32 v33, 0, v33
	v_max_f32 v66, 0, v66
	v_max_f32 v34, 0, v34
	v_max_f32 v67, 0, v67
	v_max_f32 v35, 0, v35
	s_nop 0
	v_fmac_f32_e32 v48, v121, v65
	v_fmac_f32_e32 v32, v121, v33
	v_fmac_f32_e32 v48, v122, v66
	v_fmac_f32_e32 v32, v122, v34
	v_fmac_f32_e32 v48, v123, v67
	v_fmac_f32_e32 v32, v123, v35
	v_max_f32 v68, 0, v68
	v_max_f32 v36, 0, v36
	v_max_f32 v69, 0, v69
	v_max_f32 v37, 0, v37
	v_max_f32 v70, 0, v70
	v_max_f32 v38, 0, v38
	s_nop 0
	v_fmac_f32_e32 v48, v112, v68
	v_fmac_f32_e32 v32, v112, v36
	v_fmac_f32_e32 v48, v113, v69
	v_fmac_f32_e32 v32, v113, v37
	v_fmac_f32_e32 v48, v114, v70
	v_fmac_f32_e32 v32, v114, v38
	v_max_f32 v71, 0, v71
	v_max_f32 v39, 0, v39
	v_max_f32 v72, 0, v72
	v_max_f32 v40, 0, v40
	v_max_f32 v73, 0, v73
	v_max_f32 v41, 0, v41
	s_nop 0
	v_fmac_f32_e32 v48, v115, v71
	v_fmac_f32_e32 v32, v115, v39
	v_fmac_f32_e32 v48, v104, v72
	v_fmac_f32_e32 v32, v104, v40
	v_fmac_f32_e32 v48, v105, v73
	v_fmac_f32_e32 v32, v105, v41
	v_max_f32 v74, 0, v74
	v_max_f32 v42, 0, v42
	v_max_f32 v75, 0, v75
	v_max_f32 v43, 0, v43
	v_max_f32 v76, 0, v76
	v_max_f32 v44, 0, v44
	s_nop 0
	v_fmac_f32_e32 v48, v106, v74
	v_fmac_f32_e32 v32, v106, v42
	v_fmac_f32_e32 v48, v107, v75
	v_fmac_f32_e32 v32, v107, v43
	v_fmac_f32_e32 v48, v96, v76
	v_fmac_f32_e32 v32, v96, v44
	v_max_f32 v77, 0, v77
	v_max_f32 v45, 0, v45
	v_max_f32 v78, 0, v78
	v_max_f32 v46, 0, v46
	v_max_f32 v79, 0, v79
	v_max_f32 v47, 0, v47
	s_nop 0
	v_fmac_f32_e32 v48, v97, v77
	v_fmac_f32_e32 v32, v97, v45
	v_fmac_f32_e32 v48, v98, v78
	v_fmac_f32_e32 v32, v98, v46
	v_fmac_f32_e32 v48, v99, v79
	v_fmac_f32_e32 v32, v99, v47
	s_nop 1
	v_permlane32_swap_b32_e32 v48, v32
	v_add_f32_e32 v32, v48, v32
	s_cmp_lt_u32 s92, 16
	s_cbranch_scc0 .Lidxt2_16_32
	s_cmp_lt_u32 s92, 8
	s_cbranch_scc0 .Lidxt2_8_16
	s_cmp_lt_u32 s92, 4
	s_cbranch_scc0 .Lidxt2_4_8
	s_cmp_lt_u32 s92, 2
	s_cbranch_scc0 .Lidxt2_2_4
	s_cmp_lt_u32 s92, 1
	s_cbranch_scc0 .Lidxt2_1_2
	v_mov_b32_e32 v17, v32
	s_branch .Lidxt2_join
.Lidxt2_1_2:
	v_mov_b32_e32 v0, v32
	s_branch .Lidxt2_join
.Lidxt2_2_4:
	s_cmp_lt_u32 s92, 3
	s_cbranch_scc0 .Lidxt2_3_4
	v_mov_b32_e32 v16, v32
	s_branch .Lidxt2_join
.Lidxt2_3_4:
	v_mov_b32_e32 v1, v32
	s_branch .Lidxt2_join
.Lidxt2_4_8:
	s_cmp_lt_u32 s92, 6
	s_cbranch_scc0 .Lidxt2_6_8
	s_cmp_lt_u32 s92, 5
	s_cbranch_scc0 .Lidxt2_5_6
	v_mov_b32_e32 v18, v32
	s_branch .Lidxt2_join
.Lidxt2_5_6:
	v_mov_b32_e32 v2, v32
	s_branch .Lidxt2_join
.Lidxt2_6_8:
	s_cmp_lt_u32 s92, 7
	s_cbranch_scc0 .Lidxt2_7_8
	v_mov_b32_e32 v19, v32
	s_branch .Lidxt2_join
.Lidxt2_7_8:
	v_mov_b32_e32 v3, v32
	s_branch .Lidxt2_join
.Lidxt2_8_16:
	s_cmp_lt_u32 s92, 12
	s_cbranch_scc0 .Lidxt2_12_16
	s_cmp_lt_u32 s92, 10
	s_cbranch_scc0 .Lidxt2_10_12
	s_cmp_lt_u32 s92, 9
	s_cbranch_scc0 .Lidxt2_9_10
	v_mov_b32_e32 v20, v32
	s_branch .Lidxt2_join
.Lidxt2_9_10:
	v_mov_b32_e32 v4, v32
	s_branch .Lidxt2_join
.Lidxt2_10_12:
	s_cmp_lt_u32 s92, 11
	s_cbranch_scc0 .Lidxt2_11_12
	v_mov_b32_e32 v21, v32
	s_branch .Lidxt2_join
.Lidxt2_11_12:
	v_mov_b32_e32 v5, v32
	s_branch .Lidxt2_join
.Lidxt2_12_16:
	s_cmp_lt_u32 s92, 14
	s_cbranch_scc0 .Lidxt2_14_16
	s_cmp_lt_u32 s92, 13
	s_cbranch_scc0 .Lidxt2_13_14
	v_mov_b32_e32 v22, v32
	s_branch .Lidxt2_join
.Lidxt2_13_14:
	v_mov_b32_e32 v6, v32
	s_branch .Lidxt2_join
.Lidxt2_14_16:
	s_cmp_lt_u32 s92, 15
	s_cbranch_scc0 .Lidxt2_15_16
	v_mov_b32_e32 v23, v32
	s_branch .Lidxt2_join
.Lidxt2_15_16:
	v_mov_b32_e32 v7, v32
	s_branch .Lidxt2_join
.Lidxt2_16_32:
	s_cmp_lt_u32 s92, 24
	s_cbranch_scc0 .Lidxt2_24_32
	s_cmp_lt_u32 s92, 20
	s_cbranch_scc0 .Lidxt2_20_24
	s_cmp_lt_u32 s92, 18
	s_cbranch_scc0 .Lidxt2_18_20
	s_cmp_lt_u32 s92, 17
	s_cbranch_scc0 .Lidxt2_17_18
	v_mov_b32_e32 v24, v32
	s_branch .Lidxt2_join
.Lidxt2_17_18:
	v_mov_b32_e32 v8, v32
	s_branch .Lidxt2_join
.Lidxt2_18_20:
	s_cmp_lt_u32 s92, 19
	s_cbranch_scc0 .Lidxt2_19_20
	v_mov_b32_e32 v25, v32
	s_branch .Lidxt2_join
.Lidxt2_19_20:
	v_mov_b32_e32 v11, v32
	s_branch .Lidxt2_join
.Lidxt2_20_24:
	s_cmp_lt_u32 s92, 22
	s_cbranch_scc0 .Lidxt2_22_24
	s_cmp_lt_u32 s92, 21
	s_cbranch_scc0 .Lidxt2_21_22
	v_mov_b32_e32 v26, v32
	s_branch .Lidxt2_join
.Lidxt2_21_22:
	v_mov_b32_e32 v10, v32
	s_branch .Lidxt2_join
.Lidxt2_22_24:
	s_cmp_lt_u32 s92, 23
	s_cbranch_scc0 .Lidxt2_23_24
	v_mov_b32_e32 v27, v32
	s_branch .Lidxt2_join
.Lidxt2_23_24:
	v_mov_b32_e32 v9, v32
	s_branch .Lidxt2_join
.Lidxt2_24_32:
	s_cmp_lt_u32 s92, 28
	s_cbranch_scc0 .Lidxt2_28_32
	s_cmp_lt_u32 s92, 26
	s_cbranch_scc0 .Lidxt2_26_28
	s_cmp_lt_u32 s92, 25
	s_cbranch_scc0 .Lidxt2_25_26
	v_mov_b32_e32 v28, v32
	s_branch .Lidxt2_join
.Lidxt2_25_26:
	v_mov_b32_e32 v12, v32
	s_branch .Lidxt2_join
.Lidxt2_26_28:
	s_cmp_lt_u32 s92, 27
	s_cbranch_scc0 .Lidxt2_27_28
	v_mov_b32_e32 v29, v32
	s_branch .Lidxt2_join
.Lidxt2_27_28:
	v_mov_b32_e32 v13, v32
	s_branch .Lidxt2_join
.Lidxt2_28_32:
	s_cmp_lt_u32 s92, 30
	s_cbranch_scc0 .Lidxt2_30_32
	s_cmp_lt_u32 s92, 29
	s_cbranch_scc0 .Lidxt2_29_30
	v_mov_b32_e32 v30, v32
	s_branch .Lidxt2_join
.Lidxt2_29_30:
	v_mov_b32_e32 v14, v32
	s_branch .Lidxt2_join
.Lidxt2_30_32:
	s_cmp_lt_u32 s92, 31
	s_cbranch_scc0 .Lidxt2_31_32
	v_mov_b32_e32 v31, v32
	s_branch .Lidxt2_join
.Lidxt2_31_32:
	v_mov_b32_e32 v15, v32
.Lidxt2_join:
	s_mov_b32 s92, -1

.LBB0_1179:
	s_cmp_gt_i32 s92, -1
	s_cselect_b64 s[0:1], -1, 0
	s_and_b64 s[0:1], s[84:85], s[0:1]
	s_andn2_b64 vcc, exec, s[0:1]
	s_cbranch_vccnz .LBB0_1181
	v_max_f32 v128, 0, v80
	v_max_f32 v129, 0, v81
	v_fma_f32 v128, v124, v128, 0
	v_fmac_f32_e32 v128, v125, v129
	v_max_f32 v129, 0, v48
	v_fma_f32 v124, v124, v129, 0
	v_max_f32 v129, 0, v49
	v_fmac_f32_e32 v124, v125, v129
	v_max_f32 v125, 0, v82
	v_fmac_f32_e32 v128, v126, v125
	v_max_f32 v125, 0, v50
	v_fmac_f32_e32 v124, v126, v125
	v_max_f32 v125, 0, v83
	v_max_f32 v126, 0, v65
	v_fmac_f32_e32 v128, v127, v125
	v_max_f32 v125, 0, v51
	v_fmac_f32_e32 v124, v127, v125
	v_max_f32 v125, 0, v64
	v_fma_f32 v125, v120, v125, 0
	v_fmac_f32_e32 v125, v121, v126
	v_max_f32 v126, 0, v32
	v_fma_f32 v120, v120, v126, 0
	v_max_f32 v126, 0, v33
	v_fmac_f32_e32 v120, v121, v126
	v_max_f32 v121, 0, v66
	v_fmac_f32_e32 v125, v122, v121
	v_max_f32 v121, 0, v34
	v_fmac_f32_e32 v120, v122, v121
	v_max_f32 v121, 0, v67
	v_fmac_f32_e32 v125, v123, v121
	v_max_f32 v121, 0, v35
	v_fmac_f32_e32 v120, v123, v121
	v_max_f32 v121, 0, v84
	v_fmac_f32_e32 v128, v116, v121
	v_max_f32 v121, 0, v52
	v_fmac_f32_e32 v124, v116, v121
	v_max_f32 v116, 0, v85
	v_fmac_f32_e32 v128, v117, v116
	v_max_f32 v116, 0, v53
	v_fmac_f32_e32 v124, v117, v116
	v_max_f32 v116, 0, v86
	v_fmac_f32_e32 v128, v118, v116
	v_max_f32 v116, 0, v54
	v_fmac_f32_e32 v124, v118, v116
	v_max_f32 v116, 0, v87
	v_fmac_f32_e32 v128, v119, v116
	v_max_f32 v116, 0, v55
	v_fmac_f32_e32 v124, v119, v116
	v_max_f32 v116, 0, v68
	v_fmac_f32_e32 v125, v112, v116
	v_max_f32 v116, 0, v36
	v_fmac_f32_e32 v120, v112, v116
	v_max_f32 v112, 0, v69
	v_fmac_f32_e32 v125, v113, v112
	v_max_f32 v112, 0, v37
	v_fmac_f32_e32 v120, v113, v112
	v_max_f32 v112, 0, v70
	v_fmac_f32_e32 v125, v114, v112
	v_max_f32 v112, 0, v38
	v_fmac_f32_e32 v120, v114, v112
	v_max_f32 v112, 0, v71
	v_fmac_f32_e32 v125, v115, v112
	v_max_f32 v112, 0, v39
	v_fmac_f32_e32 v120, v115, v112
	v_max_f32 v112, 0, v88
	v_fmac_f32_e32 v128, v108, v112
	v_max_f32 v112, 0, v56
	s_nop 0
	v_fmac_f32_e32 v124, v108, v112
	v_max_f32 v108, 0, v89
	s_nop 0
	v_fmac_f32_e32 v128, v109, v108
	v_max_f32 v108, 0, v57
	s_nop 0
	v_fmac_f32_e32 v124, v109, v108
	v_max_f32 v108, 0, v90
	s_nop 0
	v_fmac_f32_e32 v128, v110, v108
	v_max_f32 v108, 0, v58
	s_nop 0
	v_fmac_f32_e32 v124, v110, v108
	v_max_f32 v108, 0, v91
	s_nop 0
	v_fmac_f32_e32 v128, v111, v108
	v_max_f32 v108, 0, v59
	s_nop 0
	v_fmac_f32_e32 v124, v111, v108
	v_max_f32 v108, 0, v72
	s_nop 0
	v_fmac_f32_e32 v125, v104, v108
	v_max_f32 v108, 0, v40
	s_nop 0
	v_fmac_f32_e32 v120, v104, v108
	v_max_f32 v104, 0, v73
	s_nop 0
	v_fmac_f32_e32 v125, v105, v104
	v_max_f32 v104, 0, v41
	s_nop 0
	v_fmac_f32_e32 v120, v105, v104
	v_max_f32 v104, 0, v74
	s_nop 0
	v_fmac_f32_e32 v125, v106, v104
	v_max_f32 v104, 0, v42
	s_nop 0
	v_fmac_f32_e32 v120, v106, v104
	v_max_f32 v104, 0, v75
	s_nop 0
	v_fmac_f32_e32 v125, v107, v104
	v_max_f32 v104, 0, v43
	s_nop 0
	v_fmac_f32_e32 v120, v107, v104
	v_max_f32 v104, 0, v92
	s_nop 0
	v_fmac_f32_e32 v128, v100, v104
	v_max_f32 v104, 0, v60
	s_nop 0
	v_fmac_f32_e32 v124, v100, v104
	v_max_f32 v100, 0, v93
	s_nop 0
	v_fmac_f32_e32 v128, v101, v100
	v_max_f32 v100, 0, v61
	s_nop 0
	v_fmac_f32_e32 v124, v101, v100
	v_max_f32 v100, 0, v94
	s_nop 0
	v_fmac_f32_e32 v128, v102, v100
	v_max_f32 v100, 0, v62
	s_nop 0
	v_fmac_f32_e32 v124, v102, v100
	v_max_f32 v100, 0, v95
	s_nop 0
	v_fmac_f32_e32 v128, v103, v100
	v_max_f32 v100, 0, v63
	s_nop 0
	v_fmac_f32_e32 v124, v103, v100
	v_max_f32 v100, 0, v76
	s_nop 1
	v_permlane32_swap_b32_e32 v128, v124
	v_fmac_f32_e32 v125, v96, v100
	v_max_f32 v100, 0, v44
	s_nop 0
	v_fmac_f32_e32 v120, v96, v100
	v_max_f32 v96, 0, v77
	s_nop 0
	v_fmac_f32_e32 v125, v97, v96
	v_max_f32 v96, 0, v45
	s_nop 0
	v_fmac_f32_e32 v120, v97, v96
	v_max_f32 v96, 0, v78
	v_lshl_add_u32 v97, s92, 8, v224
	v_fmac_f32_e32 v125, v98, v96
	v_max_f32 v96, 0, v46
	s_nop 0
	v_fmac_f32_e32 v120, v98, v96
	v_max_f32 v96, 0, v79
	s_nop 0
	v_fmac_f32_e32 v125, v99, v96
	v_max_f32 v96, 0, v47
	s_nop 0
	v_fmac_f32_e32 v120, v99, v96
	v_add_f32_e32 v96, v128, v124
	s_nop 0
	v_permlane32_swap_b32_e32 v125, v120
	ds_write_b32 v97, v96
	v_add_f32_e32 v96, v125, v120
	s_cmp_lt_u32 s92, 16
	s_cbranch_scc0 .Lidxt3_16_32
	s_cmp_lt_u32 s92, 8
	s_cbranch_scc0 .Lidxt3_8_16
	s_cmp_lt_u32 s92, 4
	s_cbranch_scc0 .Lidxt3_4_8
	s_cmp_lt_u32 s92, 2
	s_cbranch_scc0 .Lidxt3_2_4
	s_cmp_lt_u32 s92, 1
	s_cbranch_scc0 .Lidxt3_1_2
	v_mov_b32_e32 v17, v96
	s_branch .Lidxt3_join
.Lidxt3_1_2:
	v_mov_b32_e32 v0, v96
	s_branch .Lidxt3_join
.Lidxt3_2_4:
	s_cmp_lt_u32 s92, 3
	s_cbranch_scc0 .Lidxt3_3_4
	v_mov_b32_e32 v16, v96
	s_branch .Lidxt3_join
.Lidxt3_3_4:
	v_mov_b32_e32 v1, v96
	s_branch .Lidxt3_join
.Lidxt3_4_8:
	s_cmp_lt_u32 s92, 6
	s_cbranch_scc0 .Lidxt3_6_8
	s_cmp_lt_u32 s92, 5
	s_cbranch_scc0 .Lidxt3_5_6
	v_mov_b32_e32 v18, v96
	s_branch .Lidxt3_join
.Lidxt3_5_6:
	v_mov_b32_e32 v2, v96
	s_branch .Lidxt3_join
.Lidxt3_6_8:
	s_cmp_lt_u32 s92, 7
	s_cbranch_scc0 .Lidxt3_7_8
	v_mov_b32_e32 v19, v96
	s_branch .Lidxt3_join
.Lidxt3_7_8:
	v_mov_b32_e32 v3, v96
	s_branch .Lidxt3_join
.Lidxt3_8_16:
	s_cmp_lt_u32 s92, 12
	s_cbranch_scc0 .Lidxt3_12_16
	s_cmp_lt_u32 s92, 10
	s_cbranch_scc0 .Lidxt3_10_12
	s_cmp_lt_u32 s92, 9
	s_cbranch_scc0 .Lidxt3_9_10
	v_mov_b32_e32 v20, v96
	s_branch .Lidxt3_join
.Lidxt3_9_10:
	v_mov_b32_e32 v4, v96
	s_branch .Lidxt3_join
.Lidxt3_10_12:
	s_cmp_lt_u32 s92, 11
	s_cbranch_scc0 .Lidxt3_11_12
	v_mov_b32_e32 v21, v96
	s_branch .Lidxt3_join
.Lidxt3_11_12:
	v_mov_b32_e32 v5, v96
	s_branch .Lidxt3_join
.Lidxt3_12_16:
	s_cmp_lt_u32 s92, 14
	s_cbranch_scc0 .Lidxt3_14_16
	s_cmp_lt_u32 s92, 13
	s_cbranch_scc0 .Lidxt3_13_14
	v_mov_b32_e32 v22, v96
	s_branch .Lidxt3_join
.Lidxt3_13_14:
	v_mov_b32_e32 v6, v96
	s_branch .Lidxt3_join
.Lidxt3_14_16:
	s_cmp_lt_u32 s92, 15
	s_cbranch_scc0 .Lidxt3_15_16
	v_mov_b32_e32 v23, v96
	s_branch .Lidxt3_join
.Lidxt3_15_16:
	v_mov_b32_e32 v7, v96
	s_branch .Lidxt3_join
.Lidxt3_16_32:
	s_cmp_lt_u32 s92, 24
	s_cbranch_scc0 .Lidxt3_24_32
	s_cmp_lt_u32 s92, 20
	s_cbranch_scc0 .Lidxt3_20_24
	s_cmp_lt_u32 s92, 18
	s_cbranch_scc0 .Lidxt3_18_20
	s_cmp_lt_u32 s92, 17
	s_cbranch_scc0 .Lidxt3_17_18
	v_mov_b32_e32 v24, v96
	s_branch .Lidxt3_join
.Lidxt3_17_18:
	v_mov_b32_e32 v8, v96
	s_branch .Lidxt3_join
.Lidxt3_18_20:
	s_cmp_lt_u32 s92, 19
	s_cbranch_scc0 .Lidxt3_19_20
	v_mov_b32_e32 v25, v96
	s_branch .Lidxt3_join
.Lidxt3_19_20:
	v_mov_b32_e32 v11, v96
	s_branch .Lidxt3_join
.Lidxt3_20_24:
	s_cmp_lt_u32 s92, 22
	s_cbranch_scc0 .Lidxt3_22_24
	s_cmp_lt_u32 s92, 21
	s_cbranch_scc0 .Lidxt3_21_22
	v_mov_b32_e32 v26, v96
	s_branch .Lidxt3_join
.Lidxt3_21_22:
	v_mov_b32_e32 v10, v96
	s_branch .Lidxt3_join
.Lidxt3_22_24:
	s_cmp_lt_u32 s92, 23
	s_cbranch_scc0 .Lidxt3_23_24
	v_mov_b32_e32 v27, v96
	s_branch .Lidxt3_join
.Lidxt3_23_24:
	v_mov_b32_e32 v9, v96
	s_branch .Lidxt3_join
.Lidxt3_24_32:
	s_cmp_lt_u32 s92, 28
	s_cbranch_scc0 .Lidxt3_28_32
	s_cmp_lt_u32 s92, 26
	s_cbranch_scc0 .Lidxt3_26_28
	s_cmp_lt_u32 s92, 25
	s_cbranch_scc0 .Lidxt3_25_26
	v_mov_b32_e32 v28, v96
	s_branch .Lidxt3_join
.Lidxt3_25_26:
	v_mov_b32_e32 v12, v96
	s_branch .Lidxt3_join
.Lidxt3_26_28:
	s_cmp_lt_u32 s92, 27
	s_cbranch_scc0 .Lidxt3_27_28
	v_mov_b32_e32 v29, v96
	s_branch .Lidxt3_join
.Lidxt3_27_28:
	v_mov_b32_e32 v13, v96
	s_branch .Lidxt3_join
.Lidxt3_28_32:
	s_cmp_lt_u32 s92, 30
	s_cbranch_scc0 .Lidxt3_30_32
	s_cmp_lt_u32 s92, 29
	s_cbranch_scc0 .Lidxt3_29_30
	v_mov_b32_e32 v30, v96
	s_branch .Lidxt3_join
.Lidxt3_29_30:
	v_mov_b32_e32 v14, v96
	s_branch .Lidxt3_join
.Lidxt3_30_32:
	s_cmp_lt_u32 s92, 31
	s_cbranch_scc0 .Lidxt3_31_32
	v_mov_b32_e32 v31, v96
	s_branch .Lidxt3_join
.Lidxt3_31_32:
	v_mov_b32_e32 v15, v96
.Lidxt3_join:
.LBB0_1181:
	v_mov_b32_e32 v128, v222
	s_or_b32 s20, s77, 1
	v_lshl_add_u32 v129, v128, 2, s3
	ds_read2st64_b32 v[126:127], v129 offset1:1
	ds_read2st64_b32 v[124:125], v129 offset0:2 offset1:3
	ds_read2st64_b32 v[122:123], v129 offset0:4 offset1:5
	ds_read2st64_b32 v[120:121], v129 offset0:6 offset1:7
	ds_read2st64_b32 v[118:119], v129 offset0:8 offset1:9
	ds_read2st64_b32 v[116:117], v129 offset0:10 offset1:11
	ds_read2st64_b32 v[114:115], v129 offset0:12 offset1:13
	ds_read2st64_b32 v[110:111], v129 offset0:14 offset1:15
	ds_read2st64_b32 v[112:113], v129 offset0:16 offset1:17
	ds_read2st64_b32 v[108:109], v129 offset0:18 offset1:19
	ds_read2st64_b32 v[106:107], v129 offset0:20 offset1:21
	ds_read2st64_b32 v[104:105], v129 offset0:22 offset1:23
	ds_read2st64_b32 v[102:103], v129 offset0:24 offset1:25
	ds_read2st64_b32 v[100:101], v129 offset0:26 offset1:27
	ds_read2st64_b32 v[98:99], v129 offset0:28 offset1:29
	ds_read2st64_b32 v[96:97], v129 offset0:30 offset1:31
	s_lshl_b64 s[0:1], s[88:89], 8
	s_add_u32 s16, s52, s0
	s_addc_u32 s17, s53, s1
	s_waitcnt lgkmcnt(0)
	s_cmpk_gt_u32 s77, 0xff
	v_add_u32_e32 v154, 0x80, v128
	v_add_u32_e32 v155, 0x100, v128
	v_add_u32_e32 v156, 0x180, v128
	v_add_u32_e32 v160, 0x380, v128
	v_add_u32_e32 v159, 0x300, v128
	v_add_u32_e32 v158, 0x280, v128
	v_add_u32_e32 v157, 0x200, v128
	v_add_u32_e32 v153, 0x3c0, v128
	v_add_u32_e32 v152, 0x340, v128
	v_add_u32_e32 v151, 0x2c0, v128
	v_add_u32_e32 v150, 0x240, v128
	v_add_u32_e32 v149, 0x1c0, v128
	v_add_u32_e32 v148, 0x140, v128
	v_add_u32_e32 v147, 0xc0, v128
	v_add_u32_e32 v146, 64, v128
	v_add_u32_e32 v145, 0x780, v128
	v_add_u32_e32 v144, 0x700, v128
	v_add_u32_e32 v143, 0x680, v128
	v_add_u32_e32 v142, 0x600, v128
	v_add_u32_e32 v141, 0x580, v128
	v_add_u32_e32 v140, 0x500, v128
	v_add_u32_e32 v139, 0x480, v128
	v_add_u32_e32 v138, 0x400, v128
	v_add_u32_e32 v137, 0x7c0, v128
	v_add_u32_e32 v136, 0x740, v128
	v_add_u32_e32 v135, 0x6c0, v128
	v_add_u32_e32 v134, 0x640, v128
	v_add_u32_e32 v133, 0x5c0, v128
	v_add_u32_e32 v132, 0x540, v128
	v_add_u32_e32 v131, 0x4c0, v128
	v_add_u32_e32 v130, 0x440, v128
	s_cselect_b64 s[6:7], -1, 0
	s_cmpk_lt_u32 s77, 0x100
	s_cbranch_scc1 .LBB0_1193
	s_waitcnt lgkmcnt(0)
	v_not_b32_e32 v161, v126
	v_cmp_gt_i32_e32 vcc, 0, v126
	s_mov_b32 s11, 0
	s_mov_b64 s[8:9], 0
	v_cndmask_b32_e64 v126, -|v126|, v161, vcc
	v_cmp_ge_i32_e32 vcc, s77, v128
	v_not_b32_e32 v161, v127
	s_nop 0
	v_cndmask_b32_e32 v126, 0, v126, vcc
	v_cmp_gt_i32_e32 vcc, 0, v127
	s_nop 1
	v_cndmask_b32_e64 v127, -|v127|, v161, vcc
	v_not_b32_e32 v161, v124
	v_cmp_gt_i32_e32 vcc, 0, v124
	s_nop 1
	v_cndmask_b32_e64 v124, -|v124|, v161, vcc
	v_cmp_ge_i32_e32 vcc, s77, v154
	v_not_b32_e32 v161, v125
	s_nop 0
	v_cndmask_b32_e32 v124, 0, v124, vcc
	v_cmp_gt_i32_e32 vcc, 0, v125
	s_nop 1
	v_cndmask_b32_e64 v125, -|v125|, v161, vcc
	v_not_b32_e32 v161, v122
	v_cmp_gt_i32_e32 vcc, 0, v122
	s_nop 1
	v_cndmask_b32_e64 v122, -|v122|, v161, vcc
	v_cmp_ge_i32_e32 vcc, s77, v155
	v_not_b32_e32 v161, v123
	s_nop 0
	v_cndmask_b32_e32 v122, 0, v122, vcc
	v_cmp_gt_i32_e32 vcc, 0, v123
	s_nop 1
	v_cndmask_b32_e64 v123, -|v123|, v161, vcc
	v_not_b32_e32 v161, v120
	v_cmp_gt_i32_e32 vcc, 0, v120
	s_nop 1
	v_cndmask_b32_e64 v120, -|v120|, v161, vcc
	v_cmp_ge_i32_e32 vcc, s77, v156
	v_not_b32_e32 v161, v121
	s_nop 0
	v_cndmask_b32_e32 v120, 0, v120, vcc
	v_cmp_gt_i32_e32 vcc, 0, v121
	s_nop 1
	v_cndmask_b32_e64 v121, -|v121|, v161, vcc
	v_not_b32_e32 v161, v118
	v_cmp_gt_i32_e32 vcc, 0, v118
	s_nop 1
	v_cndmask_b32_e64 v118, -|v118|, v161, vcc
	v_cmp_ge_i32_e32 vcc, s77, v157
	v_not_b32_e32 v161, v119
	s_nop 0
	v_cndmask_b32_e32 v118, 0, v118, vcc
	v_cmp_gt_i32_e32 vcc, 0, v119
	s_nop 1
	v_cndmask_b32_e64 v119, -|v119|, v161, vcc
	v_not_b32_e32 v161, v116
	v_cmp_gt_i32_e32 vcc, 0, v116
	s_nop 1
	v_cndmask_b32_e64 v116, -|v116|, v161, vcc
	v_cmp_ge_i32_e32 vcc, s77, v158
	v_not_b32_e32 v161, v117
	s_nop 0
	v_cndmask_b32_e32 v116, 0, v116, vcc
	v_cmp_gt_i32_e32 vcc, 0, v117
	s_nop 1
	v_cndmask_b32_e64 v117, -|v117|, v161, vcc
	v_not_b32_e32 v161, v114
	v_cmp_gt_i32_e32 vcc, 0, v114
	s_nop 1
	v_cndmask_b32_e64 v114, -|v114|, v161, vcc
	v_cmp_ge_i32_e32 vcc, s77, v159
	v_not_b32_e32 v161, v115
	s_nop 0
	v_cndmask_b32_e32 v114, 0, v114, vcc
	v_cmp_gt_i32_e32 vcc, 0, v115
	s_nop 1
	v_cndmask_b32_e64 v115, -|v115|, v161, vcc
	v_not_b32_e32 v161, v110
	v_cmp_gt_i32_e32 vcc, 0, v110
	s_nop 1
	v_cndmask_b32_e64 v110, -|v110|, v161, vcc
	v_cmp_ge_i32_e32 vcc, s77, v160
	s_nop 1
	v_cndmask_b32_e32 v110, 0, v110, vcc
	v_cmp_ge_i32_e32 vcc, s77, v146
	s_nop 1
	v_cndmask_b32_e32 v162, 0, v127, vcc
	v_cmp_ge_i32_e32 vcc, s77, v147
	s_nop 1
	v_cndmask_b32_e32 v161, 0, v125, vcc
	v_cmp_ge_i32_e32 vcc, s77, v148
	v_add_u32_e32 v164, -1, v161
	s_nop 0
	v_cndmask_b32_e32 v127, 0, v123, vcc
	v_cmp_ge_i32_e32 vcc, s77, v149
	s_nop 1
	v_cndmask_b32_e32 v125, 0, v121, vcc
	v_cmp_ge_i32_e32 vcc, s77, v150
	s_nop 1
	v_cndmask_b32_e32 v121, 0, v119, vcc
	v_cmp_ge_i32_e32 vcc, s77, v151
	v_not_b32_e32 v119, v111
	s_nop 0
	v_cndmask_b32_e32 v117, 0, v117, vcc
	v_cmp_ge_i32_e32 vcc, s77, v152
	s_nop 1
	v_cndmask_b32_e32 v115, 0, v115, vcc
	v_cmp_gt_i32_e32 vcc, 0, v111
	s_nop 1
	v_cndmask_b32_e64 v111, -|v111|, v119, vcc
	v_cmp_ge_i32_e32 vcc, s77, v153
	v_not_b32_e32 v119, v112
	s_nop 0
	v_cndmask_b32_e32 v111, 0, v111, vcc
	v_cmp_gt_i32_e32 vcc, 0, v112
	s_nop 1
	v_cndmask_b32_e64 v112, -|v112|, v119, vcc
	v_not_b32_e32 v119, v113
	v_cmp_gt_i32_e32 vcc, 0, v113
	s_nop 1
	v_cndmask_b32_e64 v113, -|v113|, v119, vcc
	v_not_b32_e32 v119, v108
	v_cmp_gt_i32_e32 vcc, 0, v108
	s_nop 1
	v_cndmask_b32_e64 v108, -|v108|, v119, vcc
	v_not_b32_e32 v119, v109
	v_cmp_gt_i32_e32 vcc, 0, v109
	s_nop 1
	v_cndmask_b32_e64 v109, -|v109|, v119, vcc
	v_not_b32_e32 v119, v106
	v_cmp_gt_i32_e32 vcc, 0, v106
	s_nop 1
	v_cndmask_b32_e64 v106, -|v106|, v119, vcc
	v_not_b32_e32 v119, v107
	v_cmp_gt_i32_e32 vcc, 0, v107
	s_nop 1
	v_cndmask_b32_e64 v107, -|v107|, v119, vcc
	v_not_b32_e32 v119, v104
	v_cmp_gt_i32_e32 vcc, 0, v104
	s_nop 1
	v_cndmask_b32_e64 v104, -|v104|, v119, vcc
	v_not_b32_e32 v119, v105
	v_cmp_gt_i32_e32 vcc, 0, v105
	s_nop 1
	v_cndmask_b32_e64 v105, -|v105|, v119, vcc
	v_not_b32_e32 v119, v102
	v_cmp_gt_i32_e32 vcc, 0, v102
	s_nop 1
	v_cndmask_b32_e64 v102, -|v102|, v119, vcc
	v_not_b32_e32 v119, v103
	v_cmp_gt_i32_e32 vcc, 0, v103
	s_nop 1
	v_cndmask_b32_e64 v103, -|v103|, v119, vcc
	v_not_b32_e32 v119, v100
	v_cmp_gt_i32_e32 vcc, 0, v100
	s_nop 1
	v_cndmask_b32_e64 v100, -|v100|, v119, vcc
	v_not_b32_e32 v119, v101
	v_cmp_gt_i32_e32 vcc, 0, v101
	s_nop 1
	v_cndmask_b32_e64 v101, -|v101|, v119, vcc
	v_not_b32_e32 v119, v98
	v_cmp_gt_i32_e32 vcc, 0, v98
	s_nop 1
	v_cndmask_b32_e64 v98, -|v98|, v119, vcc
	v_not_b32_e32 v119, v99
	v_cmp_gt_i32_e32 vcc, 0, v99
	s_nop 1
	v_cndmask_b32_e64 v163, -|v99|, v119, vcc
	v_cmp_ge_i32_e32 vcc, s77, v138
	s_nop 1
	v_cndmask_b32_e32 v119, 0, v112, vcc
	v_cmp_ge_i32_e32 vcc, s77, v139
	s_nop 1
	v_cndmask_b32_e32 v112, 0, v108, vcc
	v_cmp_ge_i32_e32 vcc, s77, v140
	s_nop 1
	v_cndmask_b32_e32 v108, 0, v106, vcc
	v_cmp_ge_i32_e32 vcc, s77, v141
	s_nop 1
	v_cndmask_b32_e32 v106, 0, v104, vcc
	v_cmp_ge_i32_e32 vcc, s77, v142
	s_nop 1
	v_cndmask_b32_e32 v104, 0, v102, vcc
	v_cmp_ge_i32_e32 vcc, s77, v143
	s_nop 1
	v_cndmask_b32_e32 v102, 0, v100, vcc
	v_cmp_ge_i32_e32 vcc, s77, v144
	s_nop 1
	v_cndmask_b32_e32 v99, 0, v98, vcc
	v_not_b32_e32 v98, v96
	v_cmp_gt_i32_e32 vcc, 0, v96
	s_nop 1
	v_cndmask_b32_e64 v96, -|v96|, v98, vcc
	v_cmp_ge_i32_e32 vcc, s77, v145
	s_nop 1
	v_cndmask_b32_e32 v98, 0, v96, vcc
	v_cmp_ge_i32_e32 vcc, s77, v130
	v_not_b32_e32 v96, v97
	s_nop 0
	v_cndmask_b32_e32 v123, 0, v113, vcc
	v_cmp_ge_i32_e32 vcc, s77, v131
	s_nop 1
	v_cndmask_b32_e32 v113, 0, v109, vcc
	v_cmp_ge_i32_e32 vcc, s77, v132
	s_nop 1
	v_cndmask_b32_e32 v109, 0, v107, vcc
	v_cmp_ge_i32_e32 vcc, s77, v133
	s_nop 1
	v_cndmask_b32_e32 v107, 0, v105, vcc
	v_cmp_ge_i32_e32 vcc, s77, v134
	s_nop 1
	v_cndmask_b32_e32 v105, 0, v103, vcc
	v_cmp_ge_i32_e32 vcc, s77, v135
	s_nop 1
	v_cndmask_b32_e32 v103, 0, v101, vcc
	v_cmp_ge_i32_e32 vcc, s77, v136
	s_nop 1
	v_cndmask_b32_e32 v101, 0, v163, vcc
	v_cmp_gt_i32_e32 vcc, 0, v97
	v_add_u32_e32 v163, -1, v162
	s_nop 0
	v_cndmask_b32_e64 v96, -|v97|, v96, vcc
	v_cmp_ge_i32_e32 vcc, s77, v137
	v_max_u32_e32 v97, v162, v126
	v_max3_u32 v97, v161, v124, v97
	v_cndmask_b32_e32 v100, 0, v96, vcc
	v_add_u32_e32 v96, -1, v126
	v_min_u32_e32 v96, v163, v96
	v_add_u32_e32 v163, -1, v124
	v_min3_u32 v96, v164, v163, v96
	v_add_u32_e32 v163, -1, v122
	v_add_u32_e32 v164, -1, v127
	v_min3_u32 v96, v164, v163, v96
	v_add_u32_e32 v163, -1, v120
	v_add_u32_e32 v164, -1, v125
	v_min3_u32 v96, v164, v163, v96
	v_add_u32_e32 v163, -1, v118
	v_add_u32_e32 v164, -1, v121
	v_min3_u32 v96, v164, v163, v96
	v_add_u32_e32 v163, -1, v116
	v_add_u32_e32 v164, -1, v117
	v_min3_u32 v96, v164, v163, v96
	v_add_u32_e32 v163, -1, v114
	v_add_u32_e32 v164, -1, v115
	v_max3_u32 v97, v127, v122, v97
	v_min3_u32 v96, v164, v163, v96
	v_add_u32_e32 v163, -1, v110
	v_add_u32_e32 v164, -1, v111
	v_max3_u32 v97, v125, v120, v97
	v_min3_u32 v96, v164, v163, v96
	v_add_u32_e32 v163, -1, v119
	v_add_u32_e32 v164, -1, v123
	v_max3_u32 v97, v121, v118, v97
	v_min3_u32 v96, v164, v163, v96
	v_add_u32_e32 v163, -1, v112
	v_add_u32_e32 v164, -1, v113
	v_max3_u32 v97, v117, v116, v97
	v_min3_u32 v96, v164, v163, v96
	v_add_u32_e32 v163, -1, v108
	v_add_u32_e32 v164, -1, v109
	v_max3_u32 v97, v115, v114, v97
	v_min3_u32 v96, v164, v163, v96
	v_add_u32_e32 v163, -1, v106
	v_add_u32_e32 v164, -1, v107
	v_max3_u32 v97, v111, v110, v97
	v_min3_u32 v96, v164, v163, v96
	v_add_u32_e32 v163, -1, v104
	v_add_u32_e32 v164, -1, v105
	v_max3_u32 v97, v123, v119, v97
	v_min3_u32 v96, v164, v163, v96
	v_add_u32_e32 v163, -1, v102
	v_add_u32_e32 v164, -1, v103
	v_max3_u32 v97, v113, v112, v97
	v_min3_u32 v96, v164, v163, v96
	v_add_u32_e32 v163, -1, v99
	v_add_u32_e32 v164, -1, v101
	v_max3_u32 v97, v109, v108, v97
	v_min3_u32 v96, v164, v163, v96
	v_add_u32_e32 v163, -1, v98
	v_add_u32_e32 v164, -1, v100
	v_max3_u32 v97, v107, v106, v97
	v_min3_u32 v96, v164, v163, v96
	v_and_b32_e32 v163, 64, v234
	v_max3_u32 v97, v105, v104, v97
	v_add_u32_e32 v163, 64, v163
	v_xor_b32_e32 v164, 1, v234
	v_max3_u32 v97, v103, v102, v97
	v_cmp_lt_i32_e32 vcc, v164, v163
	v_max3_u32 v97, v101, v99, v97
	v_max3_u32 v97, v100, v98, v97
	v_cndmask_b32_e32 v164, v234, v164, vcc
	v_lshlrev_b32_e32 v164, 2, v164
	ds_bpermute_b32 v165, v164, v97
	ds_bpermute_b32 v164, v164, v96
	s_waitcnt lgkmcnt(0)
	v_max_u32_e32 v97, v165, v97
	v_min_u32_e32 v96, v164, v96
	v_xor_b32_e32 v164, 2, v234
	v_cmp_lt_i32_e32 vcc, v164, v163
	s_nop 1
	v_cndmask_b32_e32 v164, v234, v164, vcc
	v_lshlrev_b32_e32 v164, 2, v164
	ds_bpermute_b32 v165, v164, v97
	ds_bpermute_b32 v164, v164, v96
	s_waitcnt lgkmcnt(0)
	v_max_u32_e32 v97, v165, v97
	v_min_u32_e32 v96, v164, v96
	v_xor_b32_e32 v164, 4, v234
	v_cmp_lt_i32_e32 vcc, v164, v163
	s_nop 1
	v_cndmask_b32_e32 v164, v234, v164, vcc
	v_lshlrev_b32_e32 v164, 2, v164
	ds_bpermute_b32 v165, v164, v97
	ds_bpermute_b32 v164, v164, v96
	s_waitcnt lgkmcnt(0)
	v_max_u32_e32 v97, v165, v97
	v_min_u32_e32 v96, v164, v96
	v_xor_b32_e32 v164, 8, v234
	v_cmp_lt_i32_e32 vcc, v164, v163
	s_nop 1
	v_cndmask_b32_e32 v164, v234, v164, vcc
	v_lshlrev_b32_e32 v164, 2, v164
	ds_bpermute_b32 v165, v164, v97
	ds_bpermute_b32 v164, v164, v96
	s_waitcnt lgkmcnt(0)
	v_max_u32_e32 v97, v165, v97
	v_min_u32_e32 v96, v164, v96
	v_xor_b32_e32 v164, 16, v234
	v_cmp_lt_i32_e32 vcc, v164, v163
	s_nop 1
	v_cndmask_b32_e32 v164, v234, v164, vcc
	v_lshlrev_b32_e32 v164, 2, v164
	ds_bpermute_b32 v165, v164, v97
	ds_bpermute_b32 v164, v164, v96
	s_waitcnt lgkmcnt(0)
	v_max_u32_e32 v97, v165, v97
	v_min_u32_e32 v96, v164, v96
	v_xor_b32_e32 v164, 32, v234
	v_cmp_lt_i32_e32 vcc, v164, v163
	s_nop 1
	v_cndmask_b32_e32 v163, v234, v164, vcc
	v_lshlrev_b32_e32 v163, 2, v163
	ds_bpermute_b32 v164, v163, v97
	ds_bpermute_b32 v163, v163, v96
	s_waitcnt lgkmcnt(0)
	v_max_u32_e32 v97, v164, v97
	v_min_u32_e32 v96, v163, v96
	v_readfirstlane_b32 s0, v97
	v_readfirstlane_b32 s1, v96
	s_add_i32 s10, s1, 1
	s_add_i32 s12, s0, 1
	s_sub_i32 s4, s0, s1
	s_cmp_lt_u32 s4, 2
	s_cbranch_scc1 .LBB0_1197
	s_and_b32 s5, s10, 0x7fffffff
	s_sub_i32 s1, -2, s1
	s_cmp_lt_i32 s10, 0
	s_cselect_b32 s1, s5, s1
	s_and_b32 s5, s0, 0x7fffffff
	s_not_b32 s8, s0
	s_cmp_lt_i32 s0, 0
	s_cselect_b32 s0, s5, s8
	v_mov_b32_e32 v96, s0
	v_mov_b32_e32 v97, s1
	s_mov_b32 s13, s20
	s_branch .LBB0_1185

.LBB0_1622:
	v_lshl_add_u64 v[156:157], s[0:1], 0, v[144:145]
	v_lshl_add_u64 v[66:67], v[156:157], 0, s[8:9]
	s_add_i32 m0, s63, 0x4000
	v_lshl_add_u64 v[158:159], s[0:1], 0, v[140:141]
	global_load_lds_dwordx4 v[66:67], off
	v_lshl_add_u64 v[66:67], v[158:159], 0, s[10:11]
	s_add_i32 m0, s63, 0xc000
	v_lshl_add_u64 v[160:161], s[0:1], 0, v[146:147]
	global_load_lds_dwordx4 v[66:67], off
	v_lshl_add_u64 v[66:67], v[160:161], 0, s[8:9]
	s_add_i32 m0, s63, 0x4400
	v_lshl_add_u64 v[162:163], s[0:1], 0, v[142:143]
	global_load_lds_dwordx4 v[66:67], off
	v_lshl_add_u64 v[66:67], v[162:163], 0, s[10:11]
	s_add_i32 m0, s63, 0xc400
	v_add_u32_e32 v190, v171, v172
	global_load_lds_dwordx4 v[66:67], off
	v_add_u32_e32 v191, v171, v173
	v_add_u32_e32 v192, v171, v174
	v_add_u32_e32 v193, v171, v175
	v_add_u32_e32 v194, v171, v176
	v_add_u32_e32 v195, v171, v177
	v_add_u32_e32 v196, v171, v178
	v_add_u32_e32 v197, v171, v179
	ds_read_b128 v[236:239], v190 offset:32768
	ds_read_b128 v[240:243], v190 offset:40960
	ds_read_b128 v[244:247], v191 offset:32768
	ds_read_b128 v[248:251], v191 offset:40960
	s_add_i32 s84, s82, -2
	s_waitcnt lgkmcnt(2)
	v_mfma_f32_32x32x16_f16 v[66:81], v[236:239], v[106:109], 0
	v_mfma_f32_32x32x16_f16 v[82:97], v[240:243], v[106:109], 0
	ds_read_b128 v[236:239], v192 offset:32768
	ds_read_b128 v[240:243], v192 offset:40960
	s_waitcnt lgkmcnt(2)
	v_mfma_f32_32x32x16_f16 v[66:81], v[244:247], v[98:101], v[66:81]
	v_mfma_f32_32x32x16_f16 v[82:97], v[248:251], v[98:101], v[82:97]
	ds_read_b128 v[244:247], v193 offset:32768
	ds_read_b128 v[248:251], v193 offset:40960
	s_waitcnt lgkmcnt(2)
	v_mfma_f32_32x32x16_f16 v[66:81], v[236:239], v[102:105], v[66:81]
	v_mfma_f32_32x32x16_f16 v[82:97], v[240:243], v[102:105], v[82:97]
	ds_read_b128 v[236:239], v194 offset:32768
	ds_read_b128 v[240:243], v194 offset:40960
	s_waitcnt lgkmcnt(2)
	v_mfma_f32_32x32x16_f16 v[66:81], v[244:247], v[110:113], v[66:81]
	v_mfma_f32_32x32x16_f16 v[82:97], v[248:251], v[110:113], v[82:97]
	ds_read_b128 v[244:247], v195 offset:32768
	ds_read_b128 v[248:251], v195 offset:40960
	s_waitcnt lgkmcnt(2)
	v_mfma_f32_32x32x16_f16 v[66:81], v[236:239], v[118:121], v[66:81]
	v_mfma_f32_32x32x16_f16 v[82:97], v[240:243], v[118:121], v[82:97]
	ds_read_b128 v[236:239], v196 offset:32768
	ds_read_b128 v[240:243], v196 offset:40960
	s_waitcnt lgkmcnt(2)
	v_mfma_f32_32x32x16_f16 v[66:81], v[244:247], v[122:125], v[66:81]
	v_mfma_f32_32x32x16_f16 v[82:97], v[248:251], v[122:125], v[82:97]
	ds_read_b128 v[244:247], v197 offset:32768
	ds_read_b128 v[248:251], v197 offset:40960
	s_waitcnt lgkmcnt(2)
	v_mfma_f32_32x32x16_f16 v[66:81], v[236:239], v[126:129], v[66:81]
	v_mfma_f32_32x32x16_f16 v[82:97], v[240:243], v[126:129], v[82:97]
	s_cmp_lt_i32 s84, s83
	s_waitcnt lgkmcnt(0)
	v_mfma_f32_32x32x16_f16 v[66:81], v[244:247], v[114:117], v[66:81]
	v_add_u32_e32 v198, 0, v189
	v_add_u32_e32 v164, 0x10000, v198
	ds_read_b64 v[164:165], v164
	v_mfma_f32_32x32x16_f16 v[82:97], v[248:251], v[114:117], v[82:97]
	s_cbranch_scc1 .LBB0_1624
	v_add_u32_e32 v199, 0, v65
	v_add_u32_e32 v200, 0x146fc, v199
	v_add_u32_e32 v202, 0x1467c, v199
	v_add_u32_e32 v204, 0x146f4, v199
	ds_read2_b32 v[200:201], v200 offset1:1
	ds_read2_b32 v[202:203], v202 offset1:1
	ds_read2_b32 v[204:205], v204 offset1:1
	v_add_u32_e32 v206, 0x14674, v199
	v_add_u32_e32 v208, 0x14654, v199
	s_waitcnt lgkmcnt(0)
	v_pk_add_f32 v[66:67], v[66:67], v[200:201] op_sel:[0,1] op_sel_hi:[1,0]
	v_pk_add_f32 v[82:83], v[82:83], v[202:203] op_sel:[0,1] op_sel_hi:[1,0]
	v_pk_add_f32 v[68:69], v[68:69], v[204:205] op_sel:[0,1] op_sel_hi:[1,0]
	v_add_u32_e32 v200, 0x146dc, v199
	v_add_u32_e32 v202, 0x1465c, v199
	v_add_u32_e32 v204, 0x146d4, v199
	ds_read2_b32 v[206:207], v206 offset1:1
	ds_read2_b32 v[200:201], v200 offset1:1
	ds_read2_b32 v[202:203], v202 offset1:1
	ds_read2_b32 v[204:205], v204 offset1:1
	ds_read2_b32 v[208:209], v208 offset1:1
	s_waitcnt lgkmcnt(0)
	v_pk_add_f32 v[70:71], v[70:71], v[200:201] op_sel:[0,1] op_sel_hi:[1,0]
	v_pk_add_f32 v[86:87], v[86:87], v[202:203] op_sel:[0,1] op_sel_hi:[1,0]
	v_pk_add_f32 v[72:73], v[72:73], v[204:205] op_sel:[0,1] op_sel_hi:[1,0]
	v_add_u32_e32 v200, 0x146bc, v199
	v_add_u32_e32 v202, 0x1463c, v199
	v_add_u32_e32 v204, 0x146b4, v199
	ds_read2_b32 v[200:201], v200 offset1:1
	ds_read2_b32 v[202:203], v202 offset1:1
	ds_read2_b32 v[204:205], v204 offset1:1
	v_pk_add_f32 v[84:85], v[84:85], v[206:207] op_sel:[0,1] op_sel_hi:[1,0]
	v_add_u32_e32 v206, 0x14634, v199
	s_waitcnt lgkmcnt(0)
	v_pk_add_f32 v[74:75], v[74:75], v[200:201] op_sel:[0,1] op_sel_hi:[1,0]
	v_pk_add_f32 v[90:91], v[90:91], v[202:203] op_sel:[0,1] op_sel_hi:[1,0]
	v_pk_add_f32 v[76:77], v[76:77], v[204:205] op_sel:[0,1] op_sel_hi:[1,0]
	v_add_u32_e32 v200, 0x1469c, v199
	v_add_u32_e32 v202, 0x1461c, v199
	v_add_u32_e32 v204, 0x14694, v199
	v_pk_add_f32 v[88:89], v[88:89], v[208:209] op_sel:[0,1] op_sel_hi:[1,0]
	ds_read2_b32 v[206:207], v206 offset1:1
	v_add_u32_e32 v199, 0x14614, v199
	ds_read2_b32 v[200:201], v200 offset1:1
	ds_read2_b32 v[202:203], v202 offset1:1
	ds_read2_b32 v[204:205], v204 offset1:1
	ds_read2_b32 v[208:209], v199 offset1:1
	s_waitcnt lgkmcnt(0)
	v_pk_add_f32 v[78:79], v[78:79], v[200:201] op_sel:[0,1] op_sel_hi:[1,0]
	v_pk_add_f32 v[92:93], v[92:93], v[206:207] op_sel:[0,1] op_sel_hi:[1,0]
	v_pk_add_f32 v[94:95], v[94:95], v[202:203] op_sel:[0,1] op_sel_hi:[1,0]
	v_pk_add_f32 v[80:81], v[80:81], v[204:205] op_sel:[0,1] op_sel_hi:[1,0]
	v_pk_add_f32 v[96:97], v[96:97], v[208:209] op_sel:[0,1] op_sel_hi:[1,0]

.LBB0_1626:
	ds_read_b128 v[236:239], v190 offset:49152
	ds_read_b128 v[240:243], v190 offset:57344
	ds_read_b128 v[244:247], v191 offset:49152
	ds_read_b128 v[248:251], v191 offset:57344
	s_add_i32 s84, s82, -1
	s_waitcnt lgkmcnt(2)
	v_mfma_f32_32x32x16_f16 v[82:97], v[236:239], v[106:109], 0
	v_mfma_f32_32x32x16_f16 v[66:81], v[240:243], v[106:109], 0
	ds_read_b128 v[236:239], v192 offset:49152
	ds_read_b128 v[240:243], v192 offset:57344
	s_waitcnt lgkmcnt(2)
	v_mfma_f32_32x32x16_f16 v[82:97], v[244:247], v[98:101], v[82:97]
	v_mfma_f32_32x32x16_f16 v[66:81], v[248:251], v[98:101], v[66:81]
	ds_read_b128 v[244:247], v193 offset:49152
	ds_read_b128 v[248:251], v193 offset:57344
	s_waitcnt lgkmcnt(2)
	v_mfma_f32_32x32x16_f16 v[82:97], v[236:239], v[102:105], v[82:97]
	v_mfma_f32_32x32x16_f16 v[66:81], v[240:243], v[102:105], v[66:81]
	ds_read_b128 v[236:239], v194 offset:49152
	ds_read_b128 v[240:243], v194 offset:57344
	s_waitcnt lgkmcnt(2)
	v_mfma_f32_32x32x16_f16 v[82:97], v[244:247], v[110:113], v[82:97]
	v_mfma_f32_32x32x16_f16 v[66:81], v[248:251], v[110:113], v[66:81]
	ds_read_b128 v[244:247], v195 offset:49152
	ds_read_b128 v[248:251], v195 offset:57344
	s_waitcnt lgkmcnt(2)
	v_mfma_f32_32x32x16_f16 v[82:97], v[236:239], v[118:121], v[82:97]
	v_mfma_f32_32x32x16_f16 v[66:81], v[240:243], v[118:121], v[66:81]
	ds_read_b128 v[236:239], v196 offset:49152
	ds_read_b128 v[240:243], v196 offset:57344
	s_waitcnt lgkmcnt(2)
	v_mfma_f32_32x32x16_f16 v[82:97], v[244:247], v[122:125], v[82:97]
	v_mfma_f32_32x32x16_f16 v[66:81], v[248:251], v[122:125], v[66:81]
	ds_read_b128 v[244:247], v197 offset:49152
	ds_read_b128 v[248:251], v197 offset:57344
	s_waitcnt lgkmcnt(2)
	v_mfma_f32_32x32x16_f16 v[82:97], v[236:239], v[126:129], v[82:97]
	v_mfma_f32_32x32x16_f16 v[66:81], v[240:243], v[126:129], v[66:81]
	s_cmp_lt_i32 s84, s83
	s_waitcnt lgkmcnt(0)
	v_mfma_f32_32x32x16_f16 v[82:97], v[244:247], v[114:117], v[82:97]
	v_add_u32_e32 v156, 0x10008, v198
	ds_read_b64 v[156:157], v156
	v_mfma_f32_32x32x16_f16 v[66:81], v[248:251], v[114:117], v[66:81]
	s_cbranch_scc1 .LBB0_1628
	v_add_u32_e32 v194, 0, v188
	v_add_u32_e32 v158, 0x145fc, v194
	v_add_u32_e32 v160, 0x1457c, v194
	v_add_u32_e32 v162, 0x145f4, v194
	ds_read2_b32 v[158:159], v158 offset1:1
	ds_read2_b32 v[160:161], v160 offset1:1
	ds_read2_b32 v[162:163], v162 offset1:1
	v_add_u32_e32 v190, 0x14574, v194
	v_add_u32_e32 v192, 0x14554, v194
	s_waitcnt lgkmcnt(0)
	v_pk_add_f32 v[82:83], v[82:83], v[158:159] op_sel:[0,1] op_sel_hi:[1,0]
	v_pk_add_f32 v[66:67], v[66:67], v[160:161] op_sel:[0,1] op_sel_hi:[1,0]
	v_pk_add_f32 v[84:85], v[84:85], v[162:163] op_sel:[0,1] op_sel_hi:[1,0]
	v_add_u32_e32 v158, 0x145dc, v194
	v_add_u32_e32 v160, 0x1455c, v194
	v_add_u32_e32 v162, 0x145d4, v194
	ds_read2_b32 v[190:191], v190 offset1:1
	ds_read2_b32 v[158:159], v158 offset1:1
	ds_read2_b32 v[160:161], v160 offset1:1
	ds_read2_b32 v[162:163], v162 offset1:1
	ds_read2_b32 v[192:193], v192 offset1:1
	s_waitcnt lgkmcnt(0)
	v_pk_add_f32 v[86:87], v[86:87], v[158:159] op_sel:[0,1] op_sel_hi:[1,0]
	v_pk_add_f32 v[70:71], v[70:71], v[160:161] op_sel:[0,1] op_sel_hi:[1,0]
	v_pk_add_f32 v[88:89], v[88:89], v[162:163] op_sel:[0,1] op_sel_hi:[1,0]
	v_add_u32_e32 v158, 0x145bc, v194
	v_add_u32_e32 v160, 0x1453c, v194
	v_add_u32_e32 v162, 0x145b4, v194
	ds_read2_b32 v[158:159], v158 offset1:1
	ds_read2_b32 v[160:161], v160 offset1:1
	ds_read2_b32 v[162:163], v162 offset1:1
	v_pk_add_f32 v[68:69], v[68:69], v[190:191] op_sel:[0,1] op_sel_hi:[1,0]
	v_pk_add_f32 v[72:73], v[72:73], v[192:193] op_sel:[0,1] op_sel_hi:[1,0]
	v_add_u32_e32 v190, 0x14534, v194
	s_waitcnt lgkmcnt(0)
	v_pk_add_f32 v[90:91], v[90:91], v[158:159] op_sel:[0,1] op_sel_hi:[1,0]
	v_pk_add_f32 v[74:75], v[74:75], v[160:161] op_sel:[0,1] op_sel_hi:[1,0]
	v_pk_add_f32 v[92:93], v[92:93], v[162:163] op_sel:[0,1] op_sel_hi:[1,0]
	v_add_u32_e32 v158, 0x1459c, v194
	v_add_u32_e32 v160, 0x1451c, v194
	v_add_u32_e32 v162, 0x14594, v194
	v_add_u32_e32 v192, 0x14514, v194
	ds_read2_b32 v[190:191], v190 offset1:1
	ds_read2_b32 v[158:159], v158 offset1:1
	ds_read2_b32 v[160:161], v160 offset1:1
	ds_read2_b32 v[162:163], v162 offset1:1
	ds_read2_b32 v[192:193], v192 offset1:1
	s_waitcnt lgkmcnt(0)
	v_pk_add_f32 v[94:95], v[94:95], v[158:159] op_sel:[0,1] op_sel_hi:[1,0]
	v_pk_add_f32 v[78:79], v[78:79], v[160:161] op_sel:[0,1] op_sel_hi:[1,0]
	v_pk_add_f32 v[76:77], v[76:77], v[190:191] op_sel:[0,1] op_sel_hi:[1,0]
	v_pk_add_f32 v[96:97], v[96:97], v[162:163] op_sel:[0,1] op_sel_hi:[1,0]
	v_pk_add_f32 v[80:81], v[80:81], v[192:193] op_sel:[0,1] op_sel_hi:[1,0]
